# attention K/V staging by LDS-DMA issued two tile pairs ahead (no VGPR staging or ds_write), all eight waves in step
# speedup vs baseline: 1.0167x; 1.0167x over previous
; #define ALOAD(kt) { const int key0_ = (kt) * 128; \
;     if (kc < 12) { _Pragma("unroll") for (int i = 0; i < 4; ++i) kr[i] = *(const u32x4*)(Kb + (size_t)(key0_ + krow + 32 * i) * 96 + kc * 8); } \
;     _Pragma("unroll") for (int i = 0; i < 2; ++i) vr[i] = *(const u32x4*)(Vt + (size_t)vrow * NKEY + key0_ + i * 64 + vc * 8); }
; #define ASTORE(slot) { char* sk_ = smem + (slot) * KB; char* sv_ = smem + (slot) * VB; \
;     if (kc < 12) { _Pragma("unroll") for (int i = 0; i < 4; ++i) *(u32x4*)(sk_ + kwo + i * 8192) = kr[i]; } \
;     _Pragma("unroll") for (int i = 0; i < 2; ++i) *(u32x4*)(sv_ + vwo + i * VB) = vr[i]; }
; #define ABAR() { asm volatile("s_waitcnt lgkmcnt(0)" ::: "memory"); __builtin_amdgcn_s_barrier(); asm volatile("" ::: "memory"); }
; DEV void attn_item(const P& p, int bh, int qrow0, int nkt, int outrow0, char* smem) {
;     ...
;   int vo = 0; asm volatile("" : "+v"(vo));
;   bf16x8 qf[2][3];
; #pragma unroll
;   for (int qt = 0; qt < 2; ++qt)
; #pragma unroll
;     for (int ks = 0; ks < 3; ++ks) qf[qt][ks] = *(const bf16x8*)(Qb + (size_t)(qrow0 + wid * 32 + qt * 16 + l15) * 96 + ks * 32 + lq * 8);
;   f32x4 o[4][2];
; #pragma unroll
;   for (int vt = 0; vt < 4; ++vt)
; #pragma unroll
;     for (int qt = 0; qt < 2; ++qt) o[vt][qt] = (f32x4){0.f, 0.f, 0.f, 0.f};
;   float mused[2] = {0.f, 0.f};
;   f32x4 osum[2] = {(f32x4){0.f, 0.f, 0.f, 0.f}, (f32x4){0.f, 0.f, 0.f, 0.f}};
;   const bf16x8 ones = __builtin_bit_cast(bf16x8, (u32x4){0x3f803f80u, 0x3f803f80u, 0x3f803f80u, 0x3f803f80u});
;   u32x4 kr[4], vr[2];
;   const int krow = tid >> 4, kc = tid & 15;
;   const int vrow = tid >> 3, vc = tid & 7;
;   const int kwo = vo + krow * 256 + ((kc ^ (krow & 15)) << 4), vwo = vo + VBASE + vrow * 128 + ((vc ^ ((vrow >> 1) & 7)) << 4);
;   const int kro = vo + l15 * 256, vro = vo + VBASE + l15 * 128;
;   f32x4 st[4][2];
;   bf16x8 pf[2][2], vf[2][4];
;     ...
;   ALOAD(0); ASTORE(0); if (npair > 1) ALOAD(1); ABAR();
;   int s0 = 0;
; #pragma nounroll
;   for (int kp = 0; kp < npair; ++kp) {
;     const int sn = (s0 == 4) ? 0 : s0 + 2;
;     if (kp + 1 < npair) ASTORE(sn);
;     if (kp + 2 < npair) ALOAD(kp + 2);
.LBB0_158:
	s_waitcnt lgkmcnt(0)
	s_barrier
	s_cmpk_gt_u32 s6, 0xff
	v_lshrrev_b32_e32 v1, 1, v207
	v_lshl_add_u32 v210, v207, 7, v4
	s_cselect_b64 s[4:5], -1, 0
	s_cmp_lt_i32 s23, 1
	v_xor_b32_e32 v211, v206, v1
	v_bitop3_b32 v208, v206, v1, 4 bitop3:0x36
	s_cbranch_scc1 .LBB0_214
	v_mov_b32_e32 v1, v41
	v_lshl_add_u64 v[204:205], s[2:3], 0, v[0:1]
	v_xor_b32_e32 v0, v206, v207
	v_lshlrev_b32_e32 v217, 4, v0
	v_bitop3_b32 v0, v206, v207, 4 bitop3:0x36
	v_mov_b32_e32 v42, v41
	v_mov_b32_e32 v43, v41
	v_lshlrev_b32_e32 v218, 4, v0
	v_bitop3_b32 v0, v206, v207, 8 bitop3:0x36
	v_mov_b32_e32 v40, v41
	v_mov_b32_e32 v221, 0
	v_mov_b64_e32 v[94:95], v[42:43]
	v_mov_b64_e32 v[98:99], v[42:43]
	v_mov_b64_e32 v[102:103], v[42:43]
	v_mov_b64_e32 v[106:107], v[42:43]
	v_mov_b64_e32 v[110:111], v[42:43]
	v_mov_b64_e32 v[114:115], v[42:43]
	v_mov_b64_e32 v[118:119], v[42:43]
	v_mov_b64_e32 v[122:123], v[42:43]
	v_lshl_add_u32 v214, v207, 8, v2
	v_lshlrev_b32_e32 v215, 4, v211
	v_lshlrev_b32_e32 v216, 4, v208
	v_lshlrev_b32_e32 v219, 4, v0
	s_mov_b32 s25, 0
	v_mov_b32_e32 v220, 0
	v_mov_b64_e32 v[92:93], v[40:41]
	v_mov_b64_e32 v[96:97], v[40:41]
	v_mov_b64_e32 v[100:101], v[40:41]
	v_mov_b64_e32 v[104:105], v[40:41]
	v_mov_b64_e32 v[108:109], v[40:41]
	v_mov_b64_e32 v[112:113], v[40:41]
	v_mov_b64_e32 v[116:117], v[40:41]
	v_mov_b64_e32 v[120:121], v[40:41]
	s_mov_b32 s10, 0
	s_mov_b32 s11, 0
	v_mov_b32_e32 v0, 0
	v_mov_b32_e32 v1, v221
	v_mov_b32_e32 v2, v221
	v_mov_b32_e32 v3, v221
	v_mov_b32_e32 v4, v221
	v_mov_b32_e32 v5, v221
	v_mov_b32_e32 v6, v221
	v_mov_b32_e32 v7, v221
	v_xor_b32_e32 v226, 0x80000000, v221
	v_xor_b32_e32 v230, 0x80000000, v220
	v_mov_b32_e32 v222, s56
	v_mov_b32_e32 v227, v226
	v_mov_b32_e32 v231, v230
	v_mov_b32_e32 v223, v222
	v_mov_b32_e32 v228, v226
	v_mov_b32_e32 v232, v230
	v_mov_b32_e32 v224, v222
	v_mov_b32_e32 v229, v226
	v_mov_b32_e32 v233, v230
	v_mov_b32_e32 v225, v222
	s_add_i32 s2, s10, 2
	s_cmp_lg_u32 s10, 4
	s_cselect_b32 s24, s2, 0
	s_add_i32 s26, s11, 1
	s_cmp_ge_i32 s26, s23
	s_cbranch_scc1 .Latt_i164
	s_and_saveexec_b64 s[2:3], s[38:39]
	s_cbranch_execz .Latt_i163
	v_lshl_add_u32 v8, s24, 14, v212
	s_waitcnt vmcnt(5)
	ds_write_b128 v8, v[68:71]
	s_waitcnt vmcnt(4)
	ds_write_b128 v8, v[72:75] offset:8192
	s_waitcnt vmcnt(3)
	ds_write_b128 v8, v[76:79] offset:16384
	s_waitcnt vmcnt(2)
	ds_write_b128 v8, v[80:83] offset:24576

; #define ALOAD(kt) { const int key0_ = (kt) * 128; \
;     if (kc < 12) { _Pragma("unroll") for (int i = 0; i < 4; ++i) kr[i] = *(const u32x4*)(Kb + (size_t)(key0_ + krow + 32 * i) * 96 + kc * 8); } \
;     _Pragma("unroll") for (int i = 0; i < 2; ++i) vr[i] = *(const u32x4*)(Vt + (size_t)vrow * NKEY + key0_ + i * 64 + vc * 8); }
; #define ASTORE(slot) { char* sk_ = smem + (slot) * KB; char* sv_ = smem + (slot) * VB; \
;     if (kc < 12) { _Pragma("unroll") for (int i = 0; i < 4; ++i) *(u32x4*)(sk_ + kwo + i * 8192) = kr[i]; } \
;     _Pragma("unroll") for (int i = 0; i < 2; ++i) *(u32x4*)(sv_ + vwo + i * VB) = vr[i]; }
; #define PVLOAD(slot) { const char* s = smem + (slot) * VB; \
;     _Pragma("unroll") for (int vt = 0; vt < 4; ++vt) vf[0][vt] = *(const bf16x8*)(s + vt * 2048 + vro + (((0 * 4 + lq) ^ (l15 >> 1)) << 4)); }
; DEV void attn_item(const P& p, int bh, int qrow0, int nkt, int outrow0, char* smem) {
;     ...
;   const int kwo = vo + krow * 256 + ((kc ^ (krow & 15)) << 4), vwo = vo + VBASE + vrow * 128 + ((vc ^ ((vrow >> 1) & 7)) << 4);
;   const int kro = vo + l15 * 256, vro = vo + VBASE + l15 * 128;
;   f32x4 st[4][2];
;   bf16x8 pf[2][2], vf[2][4];
;     ...
;   for (int kp = 0; kp < npair; ++kp) {
;     const int sn = (s0 == 4) ? 0 : s0 + 2;
;     if (kp + 1 < npair) ASTORE(sn);
;     if (kp + 2 < npair) ALOAD(kp + 2);
;     if (!skew) {
;       QK(s0); PVLOAD(s0); __builtin_amdgcn_sched_barrier(0); SM(kp == 0); PVMMA(s0);
.Latt_i164:
	v_lshrrev_b32_e32 v8, 6, v201
	v_and_b32_e32 v9, 15, v237
	v_lshrrev_b32_e32 v10, 4, v237
	v_readfirstlane_b32 s2, v8
	s_lshl_b32 s40, s2, 12
	s_lshl_b32 s41, s2, 10
	v_lshl_add_u32 v11, v8, 4, v10
	v_add_u32_e32 v12, 0, v10
	v_xor_b32_e32 v12, v12, v9
	v_add_u32_e32 v13, 0, v11
	v_mul_u32_u24_e32 v13, 0xc0, v13
	v_lshl_add_u32 v68, v12, 4, v13
	v_add_u32_e32 v12, 4, v10
	v_xor_b32_e32 v12, v12, v9
	v_add_u32_e32 v13, 4, v11
	v_mul_u32_u24_e32 v13, 0xc0, v13
	v_lshl_add_u32 v69, v12, 4, v13
	v_add_u32_e32 v12, 8, v10
	v_xor_b32_e32 v12, v12, v9
	v_add_u32_e32 v13, 8, v11
	v_mul_u32_u24_e32 v13, 0xc0, v13
	v_lshl_add_u32 v70, v12, 4, v13
	v_add_u32_e32 v12, 12, v10
	v_xor_b32_e32 v12, v12, v9
	v_add_u32_e32 v13, 12, v11
	v_mul_u32_u24_e32 v13, 0xc0, v13
	v_lshl_add_u32 v71, v12, 4, v13
	v_lshrrev_b32_e32 v12, 3, v237
	v_lshl_add_u32 v12, v8, 3, v12
	v_bfe_u32 v13, v12, 1, 3
	v_and_b32_e32 v14, 7, v237
	v_xor_b32_e32 v13, v13, v14
	v_mul_u32_u24_e32 v12, 0x2200, v12
	v_lshl_add_u32 v72, v13, 4, v12
	v_add_u32_e32 v73, 0x80, v72
	s_mul_i32 s6, s19, 0xcc000
	s_mul_hi_i32 s7, s19, 0xcc000
	s_add_u32 s6, s14, s6
	s_addc_u32 s7, s15, s7
	s_add_u32 s6, s6, 0xc000
	s_addc_u32 s7, s7, 0
	s_mul_i32 s8, s19, 0x88000
	s_mul_hi_i32 s9, s19, 0x88000
	s_add_u32 s8, s16, s8
	s_addc_u32 s9, s17, s9
	s_add_u32 s8, s8, 0x200
	s_addc_u32 s9, s9, 0
.Latt_loop:
	s_add_i32 s2, s10, 2
	s_cmp_lg_u32 s10, 4
	s_cselect_b32 s24, s2, 0
	s_add_i32 s26, s11, 1
	s_add_i32 s2, s11, 2
	s_cmp_ge_i32 s2, s23
	s_cbranch_scc1 .Latt_nodma
	s_add_i32 s2, s24, 2
	s_cmp_lg_u32 s24, 4
	s_cselect_b32 s2, s2, 0
	s_lshl_b32 s3, s2, 14
	s_add_i32 s3, s3, s40
	s_add_i32 m0, s3, 0x0
	s_nop 0
	global_load_lds_dwordx4 v68, s[6:7]
	s_add_i32 m0, s3, 0x400
	s_nop 0
	global_load_lds_dwordx4 v69, s[6:7]
	s_add_i32 m0, s3, 0x800
	s_nop 0
	global_load_lds_dwordx4 v70, s[6:7]
	s_add_i32 m0, s3, 0xc00
	s_nop 0
	global_load_lds_dwordx4 v71, s[6:7]
	s_lshl_b32 s3, s2, 13
	s_add_i32 s3, s3, s41
	s_add_i32 s3, s3, 0x18000
	s_mov_b32 m0, s3
	s_nop 0
	global_load_lds_dwordx4 v72, s[8:9]
	s_add_i32 m0, s3, 0x2000
	s_nop 0
	global_load_lds_dwordx4 v73, s[8:9]
	s_add_u32 s6, s6, 0x6000
	s_addc_u32 s7, s7, 0
	s_add_u32 s8, s8, 0x100
	s_addc_u32 s9, s9, 0
.Latt_nodma:
	v_lshl_add_u32 v8, s10, 14, v214
	v_add_u32_e32 v38, v8, v217
	v_add_u32_e32 v39, v8, v218
	v_add_u32_e32 v40, v8, v219
	s_lshl_b32 s27, s10, 13
	ds_read_b128 v[156:159], v38 offset:0
	ds_read_b128 v[160:163], v38 offset:4096
	ds_read_b128 v[164:167], v38 offset:8192
	ds_read_b128 v[168:171], v38 offset:12288
	ds_read_b128 v[172:175], v39 offset:0
	ds_read_b128 v[176:179], v39 offset:4096
	ds_read_b128 v[180:183], v39 offset:8192
	ds_read_b128 v[184:187], v39 offset:12288
	s_setprio 1
	s_waitcnt lgkmcnt(7)
	v_mfma_f32_16x16x32_bf16 v[140:143], v[156:159], v[44:47], v[226:229]
	v_mfma_f32_16x16x32_bf16 v[124:127], v[156:159], v[56:59], v[230:233]
	s_waitcnt lgkmcnt(6)
	v_mfma_f32_16x16x32_bf16 v[144:147], v[160:163], v[44:47], v[226:229]
	v_mfma_f32_16x16x32_bf16 v[128:131], v[160:163], v[56:59], v[230:233]
	s_waitcnt lgkmcnt(5)
	v_mfma_f32_16x16x32_bf16 v[148:151], v[164:167], v[44:47], v[226:229]
	v_mfma_f32_16x16x32_bf16 v[132:135], v[164:167], v[56:59], v[230:233]
	s_waitcnt lgkmcnt(4)
	v_mfma_f32_16x16x32_bf16 v[152:155], v[168:171], v[44:47], v[226:229]
	v_mfma_f32_16x16x32_bf16 v[136:139], v[168:171], v[56:59], v[230:233]
	s_waitcnt lgkmcnt(3)
	v_mfma_f32_16x16x32_bf16 v[140:143], v[172:175], v[48:51], v[140:143]
	v_mfma_f32_16x16x32_bf16 v[124:127], v[172:175], v[60:63], v[124:127]
	ds_read_b128 v[156:159], v40 offset:0
	ds_read_b128 v[160:163], v40 offset:4096
	ds_read_b128 v[164:167], v40 offset:8192
	ds_read_b128 v[168:171], v40 offset:12288
	s_waitcnt lgkmcnt(6)
	v_mfma_f32_16x16x32_bf16 v[144:147], v[176:179], v[48:51], v[144:147]
	v_mfma_f32_16x16x32_bf16 v[128:131], v[176:179], v[60:63], v[128:131]
	s_waitcnt lgkmcnt(5)
	v_mfma_f32_16x16x32_bf16 v[148:151], v[180:183], v[48:51], v[148:151]
	v_mfma_f32_16x16x32_bf16 v[132:135], v[180:183], v[60:63], v[132:135]
	s_waitcnt lgkmcnt(4)
	v_mfma_f32_16x16x32_bf16 v[152:155], v[184:187], v[48:51], v[152:155]
	v_mfma_f32_16x16x32_bf16 v[136:139], v[184:187], v[60:63], v[136:139]
	s_waitcnt lgkmcnt(3)
	v_mfma_f32_16x16x32_bf16 v[140:143], v[156:159], v[52:55], v[140:143]
	v_mfma_f32_16x16x32_bf16 v[124:127], v[156:159], v[64:67], v[124:127]
	s_waitcnt lgkmcnt(2)
	v_mfma_f32_16x16x32_bf16 v[144:147], v[160:163], v[52:55], v[144:147]
	v_mfma_f32_16x16x32_bf16 v[128:131], v[160:163], v[64:67], v[128:131]
	s_waitcnt lgkmcnt(1)
	v_mfma_f32_16x16x32_bf16 v[148:151], v[164:167], v[52:55], v[148:151]
	v_mfma_f32_16x16x32_bf16 v[132:135], v[164:167], v[64:67], v[132:135]
	s_waitcnt lgkmcnt(0)
	v_mfma_f32_16x16x32_bf16 v[152:155], v[168:171], v[52:55], v[152:155]
	v_mfma_f32_16x16x32_bf16 v[136:139], v[168:171], v[64:67], v[136:139]
	s_setprio 0
	v_add_u32_e32 v8, s27, v210
	v_add_u32_e32 v42, v8, v215
	v_add_u32_e32 v43, v8, v216
	v_max3_f32 v36, v140, v141, v142
	v_max3_f32 v37, v124, v125, v126
	v_max3_f32 v36, v36, v143, v144
	v_max3_f32 v37, v37, v127, v128
	v_max3_f32 v36, v36, v145, v146
	v_max3_f32 v37, v37, v129, v130
	v_max3_f32 v36, v36, v147, v148
	v_max3_f32 v37, v37, v131, v132
	v_max3_f32 v36, v36, v149, v150
	v_max3_f32 v37, v37, v133, v134
	v_max3_f32 v36, v36, v151, v152
	v_max3_f32 v37, v37, v135, v136
	v_max3_f32 v36, v36, v153, v154
	v_max3_f32 v37, v37, v137, v138
	v_max3_f32 v36, v36, v155, v155
	v_max3_f32 v37, v37, v139, v139
	v_max_f32_e32 v9, v36, v37
	v_cmp_lt_f32_e32 vcc, s44, v9
	ds_read_b128 v[16:19], v42 offset:0
	ds_read_b128 v[20:23], v42 offset:2048
	ds_read_b128 v[24:27], v42 offset:4096
	ds_read_b128 v[28:31], v42 offset:6144
	ds_read_b128 v[188:191], v43 offset:0
	ds_read_b128 v[192:195], v43 offset:2048
	ds_read_b128 v[196:199], v43 offset:4096
	ds_read_b128 v[32:35], v43 offset:6144
	s_cmp_eq_u32 s11, 0
	s_cbranch_scc1 .Latt_rare_a
	s_cbranch_vccnz .Latt_rare_a
; #define PVLOAD(slot) { const char* s = smem + (slot) * VB; \
;     _Pragma("unroll") for (int vt = 0; vt < 4; ++vt) vf[0][vt] = *(const bf16x8*)(s + vt * 2048 + vro + (((0 * 4 + lq) ^ (l15 >> 1)) << 4)); }
; DEV void attn_item(const P& p, int bh, int qrow0, int nkt, int outrow0, char* smem) {
;     ...
;       QK(s0); PVLOAD(s0); __builtin_amdgcn_sched_barrier(0); SM(kp == 0); PVMMA(s0);
;       QK(s0 + 1); PVLOAD(s0 + 1); __builtin_amdgcn_sched_barrier(0); SM(false); PVMMA(s0 + 1);
.Latt_c_a:
	v_exp_f32_e32 v140, v140
	v_exp_f32_e32 v141, v141
	v_exp_f32_e32 v142, v142
	v_exp_f32_e32 v143, v143
	v_exp_f32_e32 v144, v144
	v_exp_f32_e32 v145, v145
	v_exp_f32_e32 v146, v146
	v_exp_f32_e32 v147, v147
	v_exp_f32_e32 v124, v124
	v_exp_f32_e32 v125, v125
	v_exp_f32_e32 v126, v126
	v_exp_f32_e32 v127, v127
	v_exp_f32_e32 v128, v128
	v_exp_f32_e32 v129, v129
	v_exp_f32_e32 v130, v130
	v_exp_f32_e32 v131, v131
	v_cvt_pk_bf16_f32 v140, v140, v141
	v_cvt_pk_bf16_f32 v141, v142, v143
	v_cvt_pk_bf16_f32 v142, v144, v145
	v_cvt_pk_bf16_f32 v143, v146, v147
	v_cvt_pk_bf16_f32 v124, v124, v125
	v_cvt_pk_bf16_f32 v125, v126, v127
	v_cvt_pk_bf16_f32 v126, v128, v129
	v_cvt_pk_bf16_f32 v127, v130, v131
	s_waitcnt lgkmcnt(4)
	ds_read_b128 v[156:159], v38 offset:16384
	ds_read_b128 v[160:163], v38 offset:20480
	ds_read_b128 v[164:167], v38 offset:24576
	ds_read_b128 v[168:171], v38 offset:28672
	ds_read_b128 v[172:175], v39 offset:16384
	ds_read_b128 v[176:179], v39 offset:20480
	ds_read_b128 v[180:183], v39 offset:24576
	ds_read_b128 v[184:187], v39 offset:28672
	s_setprio 1
	s_waitcnt lgkmcnt(12)
	v_mfma_f32_16x16x32_bf16 v[92:95], v[16:19], v[140:143], v[92:95]
	v_exp_f32_e32 v148, v148
	v_exp_f32_e32 v149, v149
	v_mfma_f32_16x16x32_bf16 v[96:99], v[16:19], v[124:127], v[96:99]
	v_exp_f32_e32 v150, v150
	v_exp_f32_e32 v151, v151
	v_mfma_f32_16x16x32_bf16 v[100:103], v[20:23], v[140:143], v[100:103]
	v_exp_f32_e32 v152, v152
	v_exp_f32_e32 v153, v153
	v_mfma_f32_16x16x32_bf16 v[104:107], v[20:23], v[124:127], v[104:107]
	v_exp_f32_e32 v154, v154
	v_exp_f32_e32 v155, v155
	v_mfma_f32_16x16x32_bf16 v[108:111], v[24:27], v[140:143], v[108:111]
	v_cvt_pk_bf16_f32 v148, v148, v149
	v_cvt_pk_bf16_f32 v149, v150, v151
	v_mfma_f32_16x16x32_bf16 v[112:115], v[24:27], v[124:127], v[112:115]
	v_cvt_pk_bf16_f32 v150, v152, v153
	v_cvt_pk_bf16_f32 v151, v154, v155
	v_mfma_f32_16x16x32_bf16 v[116:119], v[28:31], v[140:143], v[116:119]
	v_exp_f32_e32 v132, v132
	v_exp_f32_e32 v133, v133
	v_mfma_f32_16x16x32_bf16 v[120:123], v[28:31], v[124:127], v[120:123]
	v_exp_f32_e32 v134, v134
	v_exp_f32_e32 v135, v135
	v_mfma_f32_16x16x32_bf16 v[0:3], v[222:225], v[140:143], v[0:3]
	v_exp_f32_e32 v136, v136
	v_exp_f32_e32 v137, v137
	v_mfma_f32_16x16x32_bf16 v[4:7], v[222:225], v[124:127], v[4:7]
	v_exp_f32_e32 v138, v138
	v_exp_f32_e32 v139, v139
	s_waitcnt lgkmcnt(8)
	v_mfma_f32_16x16x32_bf16 v[92:95], v[188:191], v[148:151], v[92:95]
	v_cvt_pk_bf16_f32 v132, v132, v133
	v_cvt_pk_bf16_f32 v133, v134, v135
	v_mfma_f32_16x16x32_bf16 v[100:103], v[192:195], v[148:151], v[100:103]
	v_cvt_pk_bf16_f32 v134, v136, v137
	v_cvt_pk_bf16_f32 v135, v138, v139
	v_mfma_f32_16x16x32_bf16 v[108:111], v[196:199], v[148:151], v[108:111]
	v_mfma_f32_16x16x32_bf16 v[116:119], v[32:35], v[148:151], v[116:119]
	v_mfma_f32_16x16x32_bf16 v[0:3], v[222:225], v[148:151], v[0:3]
	v_mfma_f32_16x16x32_bf16 v[96:99], v[188:191], v[132:135], v[96:99]
	v_mfma_f32_16x16x32_bf16 v[104:107], v[192:195], v[132:135], v[104:107]
	v_mfma_f32_16x16x32_bf16 v[112:115], v[196:199], v[132:135], v[112:115]
	v_mfma_f32_16x16x32_bf16 v[120:123], v[32:35], v[132:135], v[120:123]
	v_mfma_f32_16x16x32_bf16 v[4:7], v[222:225], v[132:135], v[4:7]
	s_setprio 0
	s_setprio 1
	s_waitcnt lgkmcnt(7)
	v_mfma_f32_16x16x32_bf16 v[140:143], v[156:159], v[44:47], v[226:229]
	v_mfma_f32_16x16x32_bf16 v[124:127], v[156:159], v[56:59], v[230:233]
	s_waitcnt lgkmcnt(6)
	v_mfma_f32_16x16x32_bf16 v[144:147], v[160:163], v[44:47], v[226:229]
	v_mfma_f32_16x16x32_bf16 v[128:131], v[160:163], v[56:59], v[230:233]
	s_waitcnt lgkmcnt(5)
	v_mfma_f32_16x16x32_bf16 v[148:151], v[164:167], v[44:47], v[226:229]
	v_mfma_f32_16x16x32_bf16 v[132:135], v[164:167], v[56:59], v[230:233]
	s_waitcnt lgkmcnt(4)
	v_mfma_f32_16x16x32_bf16 v[152:155], v[168:171], v[44:47], v[226:229]
	v_mfma_f32_16x16x32_bf16 v[136:139], v[168:171], v[56:59], v[230:233]
	s_waitcnt lgkmcnt(3)
	v_mfma_f32_16x16x32_bf16 v[140:143], v[172:175], v[48:51], v[140:143]
	v_mfma_f32_16x16x32_bf16 v[124:127], v[172:175], v[60:63], v[124:127]
	ds_read_b128 v[156:159], v40 offset:16384
	ds_read_b128 v[160:163], v40 offset:20480
	ds_read_b128 v[164:167], v40 offset:24576
	ds_read_b128 v[168:171], v40 offset:28672
	s_waitcnt lgkmcnt(6)
	v_mfma_f32_16x16x32_bf16 v[144:147], v[176:179], v[48:51], v[144:147]
	v_mfma_f32_16x16x32_bf16 v[128:131], v[176:179], v[60:63], v[128:131]
	s_waitcnt lgkmcnt(5)
	v_mfma_f32_16x16x32_bf16 v[148:151], v[180:183], v[48:51], v[148:151]
	v_mfma_f32_16x16x32_bf16 v[132:135], v[180:183], v[60:63], v[132:135]
	s_waitcnt lgkmcnt(4)
	v_mfma_f32_16x16x32_bf16 v[152:155], v[184:187], v[48:51], v[152:155]
	v_mfma_f32_16x16x32_bf16 v[136:139], v[184:187], v[60:63], v[136:139]
	s_waitcnt lgkmcnt(3)
	v_mfma_f32_16x16x32_bf16 v[140:143], v[156:159], v[52:55], v[140:143]
	v_mfma_f32_16x16x32_bf16 v[124:127], v[156:159], v[64:67], v[124:127]
	s_waitcnt lgkmcnt(2)
	v_mfma_f32_16x16x32_bf16 v[144:147], v[160:163], v[52:55], v[144:147]
	v_mfma_f32_16x16x32_bf16 v[128:131], v[160:163], v[64:67], v[128:131]
	s_waitcnt lgkmcnt(1)
	v_mfma_f32_16x16x32_bf16 v[148:151], v[164:167], v[52:55], v[148:151]
	v_mfma_f32_16x16x32_bf16 v[132:135], v[164:167], v[64:67], v[132:135]
	s_waitcnt lgkmcnt(0)
	v_mfma_f32_16x16x32_bf16 v[152:155], v[168:171], v[52:55], v[152:155]
	v_mfma_f32_16x16x32_bf16 v[136:139], v[168:171], v[64:67], v[136:139]
	s_setprio 0
	v_max3_f32 v36, v140, v141, v142
	v_max3_f32 v37, v124, v125, v126
	v_max3_f32 v36, v36, v143, v144
	v_max3_f32 v37, v37, v127, v128
	v_max3_f32 v36, v36, v145, v146
	v_max3_f32 v37, v37, v129, v130
	v_max3_f32 v36, v36, v147, v148
	v_max3_f32 v37, v37, v131, v132
	v_max3_f32 v36, v36, v149, v150
	v_max3_f32 v37, v37, v133, v134
	v_max3_f32 v36, v36, v151, v152
	v_max3_f32 v37, v37, v135, v136
	v_max3_f32 v36, v36, v153, v154
	v_max3_f32 v37, v37, v137, v138
	v_max3_f32 v36, v36, v155, v155
	v_max3_f32 v37, v37, v139, v139
	v_max_f32_e32 v9, v36, v37
	v_cmp_lt_f32_e32 vcc, s44, v9
	ds_read_b128 v[16:19], v42 offset:8192
	ds_read_b128 v[20:23], v42 offset:10240
	ds_read_b128 v[24:27], v42 offset:12288
	ds_read_b128 v[28:31], v42 offset:14336
	ds_read_b128 v[188:191], v43 offset:8192
	ds_read_b128 v[192:195], v43 offset:10240
	ds_read_b128 v[196:199], v43 offset:12288
	ds_read_b128 v[32:35], v43 offset:14336
	s_cbranch_vccnz .Latt_rare_b
; #define PVLOAD(slot) { const char* s = smem + (slot) * VB; \
;     _Pragma("unroll") for (int vt = 0; vt < 4; ++vt) vf[0][vt] = *(const bf16x8*)(s + vt * 2048 + vro + (((0 * 4 + lq) ^ (l15 >> 1)) << 4)); }
; #define ABAR() { asm volatile("s_waitcnt lgkmcnt(0)" ::: "memory"); __builtin_amdgcn_s_barrier(); asm volatile("" ::: "memory"); }
; DEV void attn_item(const P& p, int bh, int qrow0, int nkt, int outrow0, char* smem) {
;     ...
;       QK(s0 + 1); PVLOAD(s0 + 1); __builtin_amdgcn_sched_barrier(0); SM(false); PVMMA(s0 + 1);
;     ...
;     ABAR();
.Latt_c_b:
	v_exp_f32_e32 v140, v140
	v_exp_f32_e32 v141, v141
	v_exp_f32_e32 v142, v142
	v_exp_f32_e32 v143, v143
	v_exp_f32_e32 v144, v144
	v_exp_f32_e32 v145, v145
	v_exp_f32_e32 v146, v146
	v_exp_f32_e32 v147, v147
	v_exp_f32_e32 v124, v124
	v_exp_f32_e32 v125, v125
	v_exp_f32_e32 v126, v126
	v_exp_f32_e32 v127, v127
	v_exp_f32_e32 v128, v128
	v_exp_f32_e32 v129, v129
	v_exp_f32_e32 v130, v130
	v_exp_f32_e32 v131, v131
	v_cvt_pk_bf16_f32 v140, v140, v141
	v_cvt_pk_bf16_f32 v141, v142, v143
	v_cvt_pk_bf16_f32 v142, v144, v145
	v_cvt_pk_bf16_f32 v143, v146, v147
	v_cvt_pk_bf16_f32 v124, v124, v125
	v_cvt_pk_bf16_f32 v125, v126, v127
	v_cvt_pk_bf16_f32 v126, v128, v129
	v_cvt_pk_bf16_f32 v127, v130, v131
	s_setprio 1
	s_waitcnt lgkmcnt(4)
	v_mfma_f32_16x16x32_bf16 v[92:95], v[16:19], v[140:143], v[92:95]
	v_exp_f32_e32 v148, v148
	v_exp_f32_e32 v149, v149
	v_mfma_f32_16x16x32_bf16 v[96:99], v[16:19], v[124:127], v[96:99]
	v_exp_f32_e32 v150, v150
	v_exp_f32_e32 v151, v151
	v_mfma_f32_16x16x32_bf16 v[100:103], v[20:23], v[140:143], v[100:103]
	v_exp_f32_e32 v152, v152
	v_exp_f32_e32 v153, v153
	v_mfma_f32_16x16x32_bf16 v[104:107], v[20:23], v[124:127], v[104:107]
	v_exp_f32_e32 v154, v154
	v_exp_f32_e32 v155, v155
	v_mfma_f32_16x16x32_bf16 v[108:111], v[24:27], v[140:143], v[108:111]
	v_cvt_pk_bf16_f32 v148, v148, v149
	v_cvt_pk_bf16_f32 v149, v150, v151
	v_mfma_f32_16x16x32_bf16 v[112:115], v[24:27], v[124:127], v[112:115]
	v_cvt_pk_bf16_f32 v150, v152, v153
	v_cvt_pk_bf16_f32 v151, v154, v155
	v_mfma_f32_16x16x32_bf16 v[116:119], v[28:31], v[140:143], v[116:119]
	v_exp_f32_e32 v132, v132
	v_exp_f32_e32 v133, v133
	v_mfma_f32_16x16x32_bf16 v[120:123], v[28:31], v[124:127], v[120:123]
	v_exp_f32_e32 v134, v134
	v_exp_f32_e32 v135, v135
	v_mfma_f32_16x16x32_bf16 v[0:3], v[222:225], v[140:143], v[0:3]
	v_exp_f32_e32 v136, v136
	v_exp_f32_e32 v137, v137
	v_mfma_f32_16x16x32_bf16 v[4:7], v[222:225], v[124:127], v[4:7]
	v_exp_f32_e32 v138, v138
	v_exp_f32_e32 v139, v139
	s_waitcnt lgkmcnt(0)
	v_mfma_f32_16x16x32_bf16 v[92:95], v[188:191], v[148:151], v[92:95]
	v_cvt_pk_bf16_f32 v132, v132, v133
	v_cvt_pk_bf16_f32 v133, v134, v135
	v_mfma_f32_16x16x32_bf16 v[100:103], v[192:195], v[148:151], v[100:103]
	v_cvt_pk_bf16_f32 v134, v136, v137
	v_cvt_pk_bf16_f32 v135, v138, v139
	v_mfma_f32_16x16x32_bf16 v[108:111], v[196:199], v[148:151], v[108:111]
	v_mfma_f32_16x16x32_bf16 v[116:119], v[32:35], v[148:151], v[116:119]
	v_mfma_f32_16x16x32_bf16 v[0:3], v[222:225], v[148:151], v[0:3]
	v_mfma_f32_16x16x32_bf16 v[96:99], v[188:191], v[132:135], v[96:99]
	v_mfma_f32_16x16x32_bf16 v[104:107], v[192:195], v[132:135], v[104:107]
	v_mfma_f32_16x16x32_bf16 v[112:115], v[196:199], v[132:135], v[112:115]
	v_mfma_f32_16x16x32_bf16 v[120:123], v[32:35], v[132:135], v[120:123]
	v_mfma_f32_16x16x32_bf16 v[4:7], v[222:225], v[132:135], v[4:7]
	s_setprio 0
	s_add_i32 s2, s11, 2
	s_cmp_ge_i32 s2, s23
	s_cbranch_scc1 .Latt_w0
	s_waitcnt vmcnt(6)
	s_branch .Latt_wd

; #define ABAR() { asm volatile("s_waitcnt lgkmcnt(0)" ::: "memory"); __builtin_amdgcn_s_barrier(); asm volatile("" ::: "memory"); }
; DEV void attn_item(const P& p, int bh, int qrow0, int nkt, int outrow0, char* smem) {
;     ...
;     ABAR();
;     s0 = sn;
;   }
.Latt_wd:
	s_waitcnt lgkmcnt(0)
	s_barrier
	s_cmp_eq_u32 s23, s26
	s_cbranch_scc1 .Latt_exit
	s_mov_b32 s10, s24
	s_mov_b32 s11, s26
	s_branch .Latt_loop

; #define PVLOAD(slot) { const char* s = smem + (slot) * VB; \
;     _Pragma("unroll") for (int vt = 0; vt < 4; ++vt) vf[0][vt] = *(const bf16x8*)(s + vt * 2048 + vro + (((0 * 4 + lq) ^ (l15 >> 1)) << 4)); }
; #define ABAR() { asm volatile("s_waitcnt lgkmcnt(0)" ::: "memory"); __builtin_amdgcn_s_barrier(); asm volatile("" ::: "memory"); }
; DEV void attn_item(const P& p, int bh, int qrow0, int nkt, int outrow0, char* smem) {
;     ...
;   if (skew) { const int sp = (s0 == 0) ? 5 : s0 - 1; PVLOAD(sp); SM(false); PVMMA(sp); }
;   ABAR();
;     ...
;   const int h = bh & 7;
; #pragma unroll
;   for (int qt = 0; qt < 2; ++qt) {
;     const float inv = 1.0f / osum[qt][0];
;     const int row = outrow0 + wid * 32 + qt * 16 + l15;
.Latt_exit:
	s_nop 7
	v_mov_b64_e32 v[176:177], v[92:93]
	v_mov_b64_e32 v[178:179], v[94:95]
	v_mov_b64_e32 v[172:173], v[100:101]
	v_mov_b64_e32 v[174:175], v[102:103]
	v_mov_b64_e32 v[168:169], v[108:109]
	v_mov_b64_e32 v[170:171], v[110:111]
	v_mov_b64_e32 v[164:165], v[116:117]
	v_mov_b64_e32 v[166:167], v[118:119]
	v_mov_b64_e32 v[160:161], v[96:97]
	v_mov_b64_e32 v[162:163], v[98:99]
	v_mov_b64_e32 v[156:157], v[104:105]
	v_mov_b64_e32 v[158:159], v[106:107]
	v_mov_b64_e32 v[36:37], v[112:113]
	v_mov_b64_e32 v[38:39], v[114:115]
	v_mov_b64_e32 v[32:33], v[120:121]
	v_mov_b64_e32 v[34:35], v[122:123]
	v_mov_b64_e32 v[22:23], v[4:5]
	v_mov_b64_e32 v[24:25], v[6:7]
	s_branch .LBB0_149
